# in-proj K loop staging DMAs in scalar-base + 32-bit offset form (drops 16 64-bit VALU adds per iteration)
# baseline (speedup 1.0000x reference)
.LBB0_156:
	s_cmp_gt_u32 s75, 1
	s_cselect_b32 s92, 1, 0
	s_ashr_i32 s15, s14, 31
	s_lshl_b64 s[18:19], s[14:15], 19
	s_add_u32 s18, s54, s18
	s_addc_u32 s19, s55, s19
	s_and_b64 s[20:21], s[16:17], exec
	s_cselect_b32 s15, s19, s27
	s_cselect_b32 s23, s18, s26
	s_ashr_i32 s13, s12, 31
	s_lshl_b64 s[20:21], s[12:13], 19
	s_add_u32 s20, s3, s20
	s_addc_u32 s21, s68, s21
	s_and_b64 s[30:31], s[16:17], exec
	s_cselect_b32 s13, s21, s29
	s_cselect_b32 s25, s20, s28
	s_add_u32 s26, s26, 0x40080
	s_addc_u32 s27, s27, 0
	s_add_u32 s36, s28, 0x100
	s_addc_u32 s37, s29, 0
	s_mov_b32 s38, -2
	v_add_u32_e32 v172, s81, v175
	ds_read_b128 v[164:167], v172
	ds_read_b128 v[168:171], v172 offset:1024
	ds_read_b128 v[182:185], v172 offset:2048
	ds_read_b128 v[186:189], v172 offset:3072
	v_add_u32_e32 v172, s82, v175
	ds_read_b128 v[190:193], v172
	ds_read_b128 v[194:197], v172 offset:1024
	ds_read_b128 v[200:203], v172 offset:2048
	ds_read_b128 v[204:207], v172 offset:3072
	s_add_u32 s28, s26, 0xfffc0080
	s_addc_u32 s29, s27, -1
	s_cmp_eq_u32 s38, 12
	s_cselect_b32 s31, s15, s29
	s_cselect_b32 s30, s23, s28
	s_cselect_b32 s29, s13, s37
	s_cselect_b32 s28, s25, s36
	s_add_i32 m0, s71, 0xc000
	ds_read_b128 v[208:211], v180
	ds_read_b128 v[212:215], v180 offset:1024
	ds_read_b128 v[216:219], v180 offset:2048
	ds_read_b128 v[220:223], v180 offset:3072
	ds_read_b128 v[224:227], v180 offset:4096
	ds_read_b128 v[228:231], v180 offset:5120
	ds_read_b128 v[232:235], v180 offset:6144
	ds_read_b128 v[236:239], v180 offset:7168
	global_load_lds_dwordx4 v158, s[26:27]
	s_add_i32 m0, s71, 0xe000
	s_nop 0
	global_load_lds_dwordx4 v160, s[26:27]
	s_cmp_eq_u32 s92, 0
	s_cbranch_scc1 .Lp1z_w8_0
	s_waitcnt vmcnt(24)
	s_branch .Lp1z_wd_0

.Lp1z_wd_0:
	s_waitcnt lgkmcnt(0)
	s_barrier
	s_setprio 1
	s_waitcnt lgkmcnt(0)
	v_mfma_f32_16x16x32_bf16 v[124:127], v[164:167], v[208:211], 0
	v_mfma_f32_16x16x32_bf16 v[120:123], v[182:185], v[208:211], 0
	v_mfma_f32_16x16x32_bf16 v[108:111], v[164:167], v[216:219], 0
	v_mfma_f32_16x16x32_bf16 v[104:107], v[182:185], v[216:219], 0
	v_mfma_f32_16x16x32_bf16 v[92:95], v[164:167], v[224:227], 0
	v_mfma_f32_16x16x32_bf16 v[88:91], v[182:185], v[224:227], 0
	v_mfma_f32_16x16x32_bf16 v[76:79], v[164:167], v[232:235], 0
	v_mfma_f32_16x16x32_bf16 v[72:75], v[182:185], v[232:235], 0
	v_mfma_f32_16x16x32_bf16 v[124:127], v[168:171], v[212:215], v[124:127]
	v_mfma_f32_16x16x32_bf16 v[120:123], v[186:189], v[212:215], v[120:123]
	v_mfma_f32_16x16x32_bf16 v[108:111], v[168:171], v[220:223], v[108:111]
	v_mfma_f32_16x16x32_bf16 v[104:107], v[186:189], v[220:223], v[104:107]
	v_mfma_f32_16x16x32_bf16 v[92:95], v[168:171], v[228:231], v[92:95]
	v_mfma_f32_16x16x32_bf16 v[88:91], v[186:189], v[228:231], v[88:91]
	v_mfma_f32_16x16x32_bf16 v[76:79], v[168:171], v[236:239], v[76:79]
	v_mfma_f32_16x16x32_bf16 v[72:75], v[186:189], v[236:239], v[72:75]
	s_setprio 0
	s_setprio 1
	v_mfma_f32_16x16x32_bf16 v[116:119], v[190:193], v[208:211], 0
	v_mfma_f32_16x16x32_bf16 v[112:115], v[200:203], v[208:211], 0
	v_mfma_f32_16x16x32_bf16 v[100:103], v[190:193], v[216:219], 0
	v_mfma_f32_16x16x32_bf16 v[96:99], v[200:203], v[216:219], 0
	v_mfma_f32_16x16x32_bf16 v[84:87], v[190:193], v[224:227], 0
	v_mfma_f32_16x16x32_bf16 v[80:83], v[200:203], v[224:227], 0
	v_mfma_f32_16x16x32_bf16 v[68:71], v[190:193], v[232:235], 0
	v_mfma_f32_16x16x32_bf16 v[64:67], v[200:203], v[232:235], 0
	v_mfma_f32_16x16x32_bf16 v[116:119], v[194:197], v[212:215], v[116:119]
	v_mfma_f32_16x16x32_bf16 v[112:115], v[204:207], v[212:215], v[112:115]
	v_mfma_f32_16x16x32_bf16 v[100:103], v[194:197], v[220:223], v[100:103]
	v_mfma_f32_16x16x32_bf16 v[96:99], v[204:207], v[220:223], v[96:99]
	v_mfma_f32_16x16x32_bf16 v[84:87], v[194:197], v[228:231], v[84:87]
	v_mfma_f32_16x16x32_bf16 v[80:83], v[204:207], v[228:231], v[80:83]
	v_mfma_f32_16x16x32_bf16 v[68:71], v[194:197], v[236:239], v[68:71]
	v_mfma_f32_16x16x32_bf16 v[64:67], v[204:207], v[236:239], v[64:67]
	s_setprio 0
	s_barrier
	s_add_i32 s39, s81, s70
	s_mov_b32 m0, s39
	ds_read_b128 v[208:211], v180 offset:16384
	ds_read_b128 v[212:215], v180 offset:17408
	ds_read_b128 v[216:219], v180 offset:18432
	ds_read_b128 v[220:223], v180 offset:19456
	ds_read_b128 v[224:227], v180 offset:20480
	ds_read_b128 v[228:231], v180 offset:21504
	ds_read_b128 v[232:235], v180 offset:22528
	ds_read_b128 v[236:239], v180 offset:23552
	global_load_lds_dwordx4 v130, s[28:29]
	s_add_i32 m0, s39, 0x2000
	s_add_u32 s40, s28, 0x40000
	s_addc_u32 s41, s29, 0
	s_add_i32 s39, s82, s70
	global_load_lds_dwordx4 v134, s[28:29]
	s_mov_b32 m0, s39
	s_nop 0
	global_load_lds_dwordx4 v130, s[40:41]
	s_add_i32 m0, s39, 0x2000
	s_nop 0
	global_load_lds_dwordx4 v134, s[40:41]
	s_mov_b32 m0, s71
	s_nop 0
	global_load_lds_dwordx4 v128, s[30:31]
	s_mov_b32 m0, s72
	s_nop 0
	global_load_lds_dwordx4 v132, s[30:31]
	s_cmp_eq_u32 s92, 0
	s_cbranch_scc1 .Lp1z_w8_1
	s_waitcnt vmcnt(24)
	s_branch .Lp1z_wd_1

.LBB0_157:
	v_add_u32_e32 v172, s81, v175
	ds_read_b128 v[164:167], v172
	ds_read_b128 v[168:171], v172 offset:1024
	ds_read_b128 v[182:185], v172 offset:2048
	ds_read_b128 v[186:189], v172 offset:3072
	v_add_u32_e32 v172, s82, v175
	ds_read_b128 v[190:193], v172
	ds_read_b128 v[194:197], v172 offset:1024
	ds_read_b128 v[200:203], v172 offset:2048
	ds_read_b128 v[204:207], v172 offset:3072
	s_add_u32 s28, s26, 0xfffc0080
	s_addc_u32 s29, s27, -1
	s_cmp_eq_u32 s38, 12
	s_cselect_b32 s31, s15, s29
	s_cselect_b32 s30, s23, s28
	s_cselect_b32 s29, s13, s37
	s_cselect_b32 s28, s25, s36
	s_add_i32 m0, s71, 0xc000
	ds_read_b128 v[208:211], v180
	ds_read_b128 v[212:215], v180 offset:1024
	ds_read_b128 v[216:219], v180 offset:2048
	ds_read_b128 v[220:223], v180 offset:3072
	ds_read_b128 v[224:227], v180 offset:4096
	ds_read_b128 v[228:231], v180 offset:5120
	ds_read_b128 v[232:235], v180 offset:6144
	ds_read_b128 v[236:239], v180 offset:7168
	global_load_lds_dwordx4 v158, s[26:27]
	s_add_i32 m0, s71, 0xe000
	s_nop 0
	global_load_lds_dwordx4 v160, s[26:27]
	s_waitcnt vmcnt(8)
	s_waitcnt lgkmcnt(0)
	s_barrier
	s_setprio 1
	s_waitcnt lgkmcnt(0)
	v_mfma_f32_16x16x32_bf16 v[124:127], v[164:167], v[208:211], v[124:127]
	v_mfma_f32_16x16x32_bf16 v[120:123], v[182:185], v[208:211], v[120:123]
	v_mfma_f32_16x16x32_bf16 v[108:111], v[164:167], v[216:219], v[108:111]
	v_mfma_f32_16x16x32_bf16 v[104:107], v[182:185], v[216:219], v[104:107]
	v_mfma_f32_16x16x32_bf16 v[92:95], v[164:167], v[224:227], v[92:95]
	v_mfma_f32_16x16x32_bf16 v[88:91], v[182:185], v[224:227], v[88:91]
	v_mfma_f32_16x16x32_bf16 v[76:79], v[164:167], v[232:235], v[76:79]
	v_mfma_f32_16x16x32_bf16 v[72:75], v[182:185], v[232:235], v[72:75]
	v_mfma_f32_16x16x32_bf16 v[124:127], v[168:171], v[212:215], v[124:127]
	v_mfma_f32_16x16x32_bf16 v[120:123], v[186:189], v[212:215], v[120:123]
	v_mfma_f32_16x16x32_bf16 v[108:111], v[168:171], v[220:223], v[108:111]
	v_mfma_f32_16x16x32_bf16 v[104:107], v[186:189], v[220:223], v[104:107]
	v_mfma_f32_16x16x32_bf16 v[92:95], v[168:171], v[228:231], v[92:95]
	v_mfma_f32_16x16x32_bf16 v[88:91], v[186:189], v[228:231], v[88:91]
	v_mfma_f32_16x16x32_bf16 v[76:79], v[168:171], v[236:239], v[76:79]
	v_mfma_f32_16x16x32_bf16 v[72:75], v[186:189], v[236:239], v[72:75]
	s_setprio 0
	s_setprio 1
	v_mfma_f32_16x16x32_bf16 v[116:119], v[190:193], v[208:211], v[116:119]
	v_mfma_f32_16x16x32_bf16 v[112:115], v[200:203], v[208:211], v[112:115]
	v_mfma_f32_16x16x32_bf16 v[100:103], v[190:193], v[216:219], v[100:103]
	v_mfma_f32_16x16x32_bf16 v[96:99], v[200:203], v[216:219], v[96:99]
	v_mfma_f32_16x16x32_bf16 v[84:87], v[190:193], v[224:227], v[84:87]
	v_mfma_f32_16x16x32_bf16 v[80:83], v[200:203], v[224:227], v[80:83]
	v_mfma_f32_16x16x32_bf16 v[68:71], v[190:193], v[232:235], v[68:71]
	v_mfma_f32_16x16x32_bf16 v[64:67], v[200:203], v[232:235], v[64:67]
	v_mfma_f32_16x16x32_bf16 v[116:119], v[194:197], v[212:215], v[116:119]
	v_mfma_f32_16x16x32_bf16 v[112:115], v[204:207], v[212:215], v[112:115]
	v_mfma_f32_16x16x32_bf16 v[100:103], v[194:197], v[220:223], v[100:103]
	v_mfma_f32_16x16x32_bf16 v[96:99], v[204:207], v[220:223], v[96:99]
	v_mfma_f32_16x16x32_bf16 v[84:87], v[194:197], v[228:231], v[84:87]
	v_mfma_f32_16x16x32_bf16 v[80:83], v[204:207], v[228:231], v[80:83]
	v_mfma_f32_16x16x32_bf16 v[68:71], v[194:197], v[236:239], v[68:71]
	v_mfma_f32_16x16x32_bf16 v[64:67], v[204:207], v[236:239], v[64:67]
	s_setprio 0
	s_barrier
	s_add_i32 s39, s81, s70
	s_mov_b32 m0, s39
	ds_read_b128 v[208:211], v180 offset:16384
	ds_read_b128 v[212:215], v180 offset:17408
	ds_read_b128 v[216:219], v180 offset:18432
	ds_read_b128 v[220:223], v180 offset:19456
	ds_read_b128 v[224:227], v180 offset:20480
	ds_read_b128 v[228:231], v180 offset:21504
	ds_read_b128 v[232:235], v180 offset:22528
	ds_read_b128 v[236:239], v180 offset:23552
	global_load_lds_dwordx4 v130, s[28:29]
	s_add_i32 m0, s39, 0x2000
	s_add_u32 s40, s28, 0x40000
	s_addc_u32 s41, s29, 0
	s_add_i32 s39, s82, s70
	global_load_lds_dwordx4 v134, s[28:29]
	s_mov_b32 m0, s39
	s_nop 0
	global_load_lds_dwordx4 v130, s[40:41]
	s_add_i32 m0, s39, 0x2000
	s_nop 0
	global_load_lds_dwordx4 v134, s[40:41]
	s_mov_b32 m0, s71
	s_nop 0
	global_load_lds_dwordx4 v128, s[30:31]
	s_mov_b32 m0, s72
	s_nop 0
	global_load_lds_dwordx4 v132, s[30:31]
	s_waitcnt vmcnt(8)
	s_waitcnt lgkmcnt(0)
	s_barrier
	s_setprio 1
	s_waitcnt lgkmcnt(0)
	v_mfma_f32_16x16x32_bf16 v[60:63], v[164:167], v[208:211], v[60:63]
	v_mfma_f32_16x16x32_bf16 v[56:59], v[182:185], v[208:211], v[56:59]
	v_mfma_f32_16x16x32_bf16 v[44:47], v[164:167], v[216:219], v[44:47]
	v_mfma_f32_16x16x32_bf16 v[40:43], v[182:185], v[216:219], v[40:43]
	v_mfma_f32_16x16x32_bf16 v[28:31], v[164:167], v[224:227], v[28:31]
	v_mfma_f32_16x16x32_bf16 v[24:27], v[182:185], v[224:227], v[24:27]
	v_mfma_f32_16x16x32_bf16 v[12:15], v[164:167], v[232:235], v[12:15]
	v_mfma_f32_16x16x32_bf16 v[8:11], v[182:185], v[232:235], v[8:11]
	v_mfma_f32_16x16x32_bf16 v[60:63], v[168:171], v[212:215], v[60:63]
	v_mfma_f32_16x16x32_bf16 v[56:59], v[186:189], v[212:215], v[56:59]
	v_mfma_f32_16x16x32_bf16 v[44:47], v[168:171], v[220:223], v[44:47]
	v_mfma_f32_16x16x32_bf16 v[40:43], v[186:189], v[220:223], v[40:43]
	v_mfma_f32_16x16x32_bf16 v[28:31], v[168:171], v[228:231], v[28:31]
	v_mfma_f32_16x16x32_bf16 v[24:27], v[186:189], v[228:231], v[24:27]
	v_mfma_f32_16x16x32_bf16 v[12:15], v[168:171], v[236:239], v[12:15]
	v_mfma_f32_16x16x32_bf16 v[8:11], v[186:189], v[236:239], v[8:11]
	s_setprio 0
	s_setprio 1
	v_mfma_f32_16x16x32_bf16 v[52:55], v[190:193], v[208:211], v[52:55]
	v_mfma_f32_16x16x32_bf16 v[48:51], v[200:203], v[208:211], v[48:51]
	v_mfma_f32_16x16x32_bf16 v[36:39], v[190:193], v[216:219], v[36:39]
	v_mfma_f32_16x16x32_bf16 v[32:35], v[200:203], v[216:219], v[32:35]
	v_mfma_f32_16x16x32_bf16 v[20:23], v[190:193], v[224:227], v[20:23]
	v_mfma_f32_16x16x32_bf16 v[16:19], v[200:203], v[224:227], v[16:19]
	v_mfma_f32_16x16x32_bf16 v[4:7], v[190:193], v[232:235], v[4:7]
	v_mfma_f32_16x16x32_bf16 v[0:3], v[200:203], v[232:235], v[0:3]
	v_mfma_f32_16x16x32_bf16 v[52:55], v[194:197], v[212:215], v[52:55]
	v_mfma_f32_16x16x32_bf16 v[48:51], v[204:207], v[212:215], v[48:51]
	v_mfma_f32_16x16x32_bf16 v[36:39], v[194:197], v[220:223], v[36:39]
	v_mfma_f32_16x16x32_bf16 v[32:35], v[204:207], v[220:223], v[32:35]
	v_mfma_f32_16x16x32_bf16 v[20:23], v[194:197], v[228:231], v[20:23]
	v_mfma_f32_16x16x32_bf16 v[16:19], v[204:207], v[228:231], v[16:19]
	v_mfma_f32_16x16x32_bf16 v[4:7], v[194:197], v[236:239], v[4:7]
	v_mfma_f32_16x16x32_bf16 v[0:3], v[204:207], v[236:239], v[0:3]
	s_setprio 0
	s_barrier
.Lp1_seg3:
	s_add_i32 s39, 0, 0x18000
	s_add_i32 s40, 0, 0x1c000
	v_add_u32_e32 v186, s39, v175
	v_add_u32_e32 v199, s40, v175
	ds_read_b128 v[164:167], v186
	ds_read_b128 v[168:171], v186 offset:1024
	ds_read_b128 v[182:185], v186 offset:2048
	ds_read_b128 v[186:189], v186 offset:3072
	ds_read_b128 v[190:193], v199
	ds_read_b128 v[194:197], v199 offset:1024
	ds_read_b128 v[200:203], v199 offset:2048
	ds_read_b128 v[204:207], v199 offset:3072
	s_add_u32 s88, s30, 0x80
	s_addc_u32 s89, s31, 0
	s_add_u32 s30, s30, 0x40000
	s_addc_u32 s31, s31, 0
	s_mov_b32 m0, s73
	ds_read_b128 v[208:211], v180 offset:32768
	ds_read_b128 v[212:215], v180 offset:33792
	ds_read_b128 v[216:219], v180 offset:34816
	ds_read_b128 v[220:223], v180 offset:35840
	ds_read_b128 v[224:227], v180 offset:36864
	ds_read_b128 v[228:231], v180 offset:37888
	ds_read_b128 v[232:235], v180 offset:38912
	ds_read_b128 v[236:239], v180 offset:39936
	global_load_lds_dwordx4 v128, s[30:31]
	s_mov_b32 m0, s74
	s_nop 0
	global_load_lds_dwordx4 v132, s[30:31]
	s_waitcnt vmcnt(8)
	s_waitcnt lgkmcnt(0)
	s_barrier
	s_setprio 1
	s_waitcnt lgkmcnt(0)
	v_mfma_f32_16x16x32_bf16 v[124:127], v[164:167], v[208:211], v[124:127]
	v_mfma_f32_16x16x32_bf16 v[120:123], v[182:185], v[208:211], v[120:123]
	v_mfma_f32_16x16x32_bf16 v[108:111], v[164:167], v[216:219], v[108:111]
	v_mfma_f32_16x16x32_bf16 v[104:107], v[182:185], v[216:219], v[104:107]
	v_mfma_f32_16x16x32_bf16 v[92:95], v[164:167], v[224:227], v[92:95]
	v_mfma_f32_16x16x32_bf16 v[88:91], v[182:185], v[224:227], v[88:91]
	v_mfma_f32_16x16x32_bf16 v[76:79], v[164:167], v[232:235], v[76:79]
	v_mfma_f32_16x16x32_bf16 v[72:75], v[182:185], v[232:235], v[72:75]
	v_mfma_f32_16x16x32_bf16 v[124:127], v[168:171], v[212:215], v[124:127]
	v_mfma_f32_16x16x32_bf16 v[120:123], v[186:189], v[212:215], v[120:123]
	v_mfma_f32_16x16x32_bf16 v[108:111], v[168:171], v[220:223], v[108:111]
	v_mfma_f32_16x16x32_bf16 v[104:107], v[186:189], v[220:223], v[104:107]
	v_mfma_f32_16x16x32_bf16 v[92:95], v[168:171], v[228:231], v[92:95]
	v_mfma_f32_16x16x32_bf16 v[88:91], v[186:189], v[228:231], v[88:91]
	v_mfma_f32_16x16x32_bf16 v[76:79], v[168:171], v[236:239], v[76:79]
	v_mfma_f32_16x16x32_bf16 v[72:75], v[186:189], v[236:239], v[72:75]
	s_setprio 0
	s_setprio 1
	v_mfma_f32_16x16x32_bf16 v[116:119], v[190:193], v[208:211], v[116:119]
	v_mfma_f32_16x16x32_bf16 v[112:115], v[200:203], v[208:211], v[112:115]
	v_mfma_f32_16x16x32_bf16 v[100:103], v[190:193], v[216:219], v[100:103]
	v_mfma_f32_16x16x32_bf16 v[96:99], v[200:203], v[216:219], v[96:99]
	v_mfma_f32_16x16x32_bf16 v[84:87], v[190:193], v[224:227], v[84:87]
	v_mfma_f32_16x16x32_bf16 v[80:83], v[200:203], v[224:227], v[80:83]
	v_mfma_f32_16x16x32_bf16 v[68:71], v[190:193], v[232:235], v[68:71]
	v_mfma_f32_16x16x32_bf16 v[64:67], v[200:203], v[232:235], v[64:67]
	v_mfma_f32_16x16x32_bf16 v[116:119], v[194:197], v[212:215], v[116:119]
	v_mfma_f32_16x16x32_bf16 v[112:115], v[204:207], v[212:215], v[112:115]
	v_mfma_f32_16x16x32_bf16 v[100:103], v[194:197], v[220:223], v[100:103]
	v_mfma_f32_16x16x32_bf16 v[96:99], v[204:207], v[220:223], v[96:99]
	v_mfma_f32_16x16x32_bf16 v[84:87], v[194:197], v[228:231], v[84:87]
	v_mfma_f32_16x16x32_bf16 v[80:83], v[204:207], v[228:231], v[80:83]
	v_mfma_f32_16x16x32_bf16 v[68:71], v[194:197], v[236:239], v[68:71]
	v_mfma_f32_16x16x32_bf16 v[64:67], v[204:207], v[236:239], v[64:67]
	s_setprio 0
	s_barrier
	s_add_u32 s90, s28, 0x80
	s_addc_u32 s91, s29, 0
	s_add_i32 s30, s39, s70
	s_mov_b32 m0, s30
	ds_read_b128 v[208:211], v180 offset:49152
	ds_read_b128 v[212:215], v180 offset:50176
	ds_read_b128 v[216:219], v180 offset:51200
	ds_read_b128 v[220:223], v180 offset:52224
	ds_read_b128 v[224:227], v180 offset:53248
	ds_read_b128 v[228:231], v180 offset:54272
	ds_read_b128 v[232:235], v180 offset:55296
	ds_read_b128 v[236:239], v180 offset:56320
	global_load_lds_dwordx4 v130, s[90:91]
	s_add_i32 m0, s30, 0x2000
	s_add_u32 s28, s28, 0x40080
	s_addc_u32 s29, s29, 0
	s_add_i32 s30, s40, s70
	global_load_lds_dwordx4 v134, s[90:91]
	s_mov_b32 m0, s30
	s_nop 0
	global_load_lds_dwordx4 v130, s[28:29]
	s_add_i32 m0, s30, 0x2000
	s_nop 0
	global_load_lds_dwordx4 v134, s[28:29]
	s_mov_b32 m0, s76
	s_nop 0
	global_load_lds_dwordx4 v128, s[88:89]
	s_mov_b32 m0, s77
	s_nop 0
	global_load_lds_dwordx4 v132, s[88:89]
	s_waitcnt vmcnt(8)
	s_waitcnt lgkmcnt(0)
	s_barrier
	s_setprio 1
	s_waitcnt lgkmcnt(0)
	v_mfma_f32_16x16x32_bf16 v[60:63], v[164:167], v[208:211], v[60:63]
	v_mfma_f32_16x16x32_bf16 v[56:59], v[182:185], v[208:211], v[56:59]
	v_mfma_f32_16x16x32_bf16 v[44:47], v[164:167], v[216:219], v[44:47]
	v_mfma_f32_16x16x32_bf16 v[40:43], v[182:185], v[216:219], v[40:43]
	v_mfma_f32_16x16x32_bf16 v[28:31], v[164:167], v[224:227], v[28:31]
	v_mfma_f32_16x16x32_bf16 v[24:27], v[182:185], v[224:227], v[24:27]
	v_mfma_f32_16x16x32_bf16 v[12:15], v[164:167], v[232:235], v[12:15]
	v_mfma_f32_16x16x32_bf16 v[8:11], v[182:185], v[232:235], v[8:11]
	v_mfma_f32_16x16x32_bf16 v[60:63], v[168:171], v[212:215], v[60:63]
	v_mfma_f32_16x16x32_bf16 v[56:59], v[186:189], v[212:215], v[56:59]
	v_mfma_f32_16x16x32_bf16 v[44:47], v[168:171], v[220:223], v[44:47]
	v_mfma_f32_16x16x32_bf16 v[40:43], v[186:189], v[220:223], v[40:43]
	v_mfma_f32_16x16x32_bf16 v[28:31], v[168:171], v[228:231], v[28:31]
	v_mfma_f32_16x16x32_bf16 v[24:27], v[186:189], v[228:231], v[24:27]
	v_mfma_f32_16x16x32_bf16 v[12:15], v[168:171], v[236:239], v[12:15]
	v_mfma_f32_16x16x32_bf16 v[8:11], v[186:189], v[236:239], v[8:11]
	s_setprio 0
	s_setprio 1
	v_mfma_f32_16x16x32_bf16 v[52:55], v[190:193], v[208:211], v[52:55]
	v_mfma_f32_16x16x32_bf16 v[48:51], v[200:203], v[208:211], v[48:51]
	v_mfma_f32_16x16x32_bf16 v[36:39], v[190:193], v[216:219], v[36:39]
	v_mfma_f32_16x16x32_bf16 v[32:35], v[200:203], v[216:219], v[32:35]
	v_mfma_f32_16x16x32_bf16 v[20:23], v[190:193], v[224:227], v[20:23]
	v_mfma_f32_16x16x32_bf16 v[16:19], v[200:203], v[224:227], v[16:19]
	v_mfma_f32_16x16x32_bf16 v[4:7], v[190:193], v[232:235], v[4:7]
	v_mfma_f32_16x16x32_bf16 v[0:3], v[200:203], v[232:235], v[0:3]
	v_mfma_f32_16x16x32_bf16 v[52:55], v[194:197], v[212:215], v[52:55]
	v_mfma_f32_16x16x32_bf16 v[48:51], v[204:207], v[212:215], v[48:51]
	v_mfma_f32_16x16x32_bf16 v[36:39], v[194:197], v[220:223], v[36:39]
	v_mfma_f32_16x16x32_bf16 v[32:35], v[204:207], v[220:223], v[32:35]
	v_mfma_f32_16x16x32_bf16 v[20:23], v[194:197], v[228:231], v[20:23]
	v_mfma_f32_16x16x32_bf16 v[16:19], v[204:207], v[228:231], v[16:19]
	v_mfma_f32_16x16x32_bf16 v[4:7], v[194:197], v[236:239], v[4:7]
	v_mfma_f32_16x16x32_bf16 v[0:3], v[204:207], v[236:239], v[0:3]
	s_setprio 0
	s_barrier
	s_add_i32 s38, s38, 2
	s_add_u32 s26, s26, 0x100
	s_addc_u32 s27, s27, 0
	s_add_u32 s36, s36, 0x100
	s_addc_u32 s37, s37, 0
	s_cmp_gt_u32 s38, 13
	s_cbranch_scc0 .LBB0_157
	s_and_b64 vcc, exec, s[10:11]
	s_cbranch_vccz .LBB0_160
	s_barrier
